# prologue ln-folded weight transposes: 4x8 row loads per item issued up front (one exposed latency instead of four)
# speedup vs baseline: 1.0075x; 1.0075x over previous
; __device__ __forceinline__ unsigned cvtpk(float lo, float hi) { f32x2_t v = {lo, hi}; bf16x2_t b = __builtin_convertvector(v, bf16x2_t); return __builtin_bit_cast(unsigned, b); }
; __device__ __forceinline__ float bf2f(unsigned b) { return __uint_as_float(b << 16); }
; __device__ __forceinline__ void transpose_item_ln(const float* W, int K, int N, bf16* WT, int mode, LAS float* scr, int item, int lane, const float* gk, const float* bk, float* part) {
;     ...
;     float s1 = 0.f, s2 = 0.f;
; #pragma unroll 8
;     for (int i = 0; i < 32; ++i) { const int kk = 2 * i + (lane >> 5); const float w = W[(size_t)(k0 + kk) * N + nsrc]; const float wg = w * gs[kk];
;         scr[kk * 33 + (lane & 31)] = wg; s1 += bf2f(cvtpk(wg, 0.f) & 0xffffu); s2 += bs[kk] * w; }
;     s1 += __shfl_xor(s1, 32); s2 += __shfl_xor(s2, 32);
;     if (lane < 32) { float* pp = part + ((size_t)kb * NC12 + n0 + lane) * 2; pp[0] = s1; pp[1] = s2; }
.LBB0_37:
	v_lshl_add_u64 v[188:189], v[18:19], 0, s[0:1]
	global_load_dword v156, v[188:189], off
	v_lshl_add_u64 v[190:191], v[30:31], 0, s[0:1]
	global_load_dword v157, v[190:191], off
	v_lshl_add_u64 v[188:189], v[28:29], 0, s[0:1]
	global_load_dword v158, v[188:189], off
	v_lshl_add_u64 v[190:191], v[26:27], 0, s[0:1]
	global_load_dword v159, v[190:191], off
	v_lshl_add_u64 v[188:189], v[24:25], 0, s[0:1]
	global_load_dword v160, v[188:189], off
	v_lshl_add_u64 v[190:191], v[22:23], 0, s[0:1]
	global_load_dword v161, v[190:191], off
	v_lshl_add_u64 v[188:189], v[20:21], 0, s[0:1]
	global_load_dword v162, v[188:189], off
	v_lshl_add_u64 v[190:191], v[14:15], 0, s[0:1]
	global_load_dword v163, v[190:191], off
	s_add_u32 s0, s0, 0x58000
	s_addc_u32 s1, s1, 0
	v_lshl_add_u64 v[188:189], v[18:19], 0, s[0:1]
	global_load_dword v164, v[188:189], off
	v_lshl_add_u64 v[190:191], v[30:31], 0, s[0:1]
	global_load_dword v165, v[190:191], off
	v_lshl_add_u64 v[188:189], v[28:29], 0, s[0:1]
	global_load_dword v166, v[188:189], off
	v_lshl_add_u64 v[190:191], v[26:27], 0, s[0:1]
	global_load_dword v167, v[190:191], off
	v_lshl_add_u64 v[188:189], v[24:25], 0, s[0:1]
	global_load_dword v168, v[188:189], off
	v_lshl_add_u64 v[190:191], v[22:23], 0, s[0:1]
	global_load_dword v169, v[190:191], off
	v_lshl_add_u64 v[188:189], v[20:21], 0, s[0:1]
	global_load_dword v170, v[188:189], off
	v_lshl_add_u64 v[190:191], v[14:15], 0, s[0:1]
	global_load_dword v171, v[190:191], off
	s_add_u32 s0, s0, 0x58000
	s_addc_u32 s1, s1, 0
	v_lshl_add_u64 v[188:189], v[18:19], 0, s[0:1]
	global_load_dword v172, v[188:189], off
	v_lshl_add_u64 v[190:191], v[30:31], 0, s[0:1]
	global_load_dword v173, v[190:191], off
	v_lshl_add_u64 v[188:189], v[28:29], 0, s[0:1]
	global_load_dword v174, v[188:189], off
	v_lshl_add_u64 v[190:191], v[26:27], 0, s[0:1]
	global_load_dword v175, v[190:191], off
	v_lshl_add_u64 v[188:189], v[24:25], 0, s[0:1]
	global_load_dword v176, v[188:189], off
	v_lshl_add_u64 v[190:191], v[22:23], 0, s[0:1]
	global_load_dword v177, v[190:191], off
	v_lshl_add_u64 v[188:189], v[20:21], 0, s[0:1]
	global_load_dword v178, v[188:189], off
	v_lshl_add_u64 v[190:191], v[14:15], 0, s[0:1]
	global_load_dword v179, v[190:191], off
	s_add_u32 s0, s0, 0x58000
	s_addc_u32 s1, s1, 0
	v_lshl_add_u64 v[188:189], v[18:19], 0, s[0:1]
	global_load_dword v180, v[188:189], off
	v_lshl_add_u64 v[190:191], v[30:31], 0, s[0:1]
	global_load_dword v181, v[190:191], off
	v_lshl_add_u64 v[188:189], v[28:29], 0, s[0:1]
	global_load_dword v182, v[188:189], off
	v_lshl_add_u64 v[190:191], v[26:27], 0, s[0:1]
	global_load_dword v183, v[190:191], off
	v_lshl_add_u64 v[188:189], v[24:25], 0, s[0:1]
	global_load_dword v184, v[188:189], off
	v_lshl_add_u64 v[190:191], v[22:23], 0, s[0:1]
	global_load_dword v185, v[190:191], off
	v_lshl_add_u64 v[188:189], v[20:21], 0, s[0:1]
	global_load_dword v186, v[188:189], off
	v_lshl_add_u64 v[190:191], v[14:15], 0, s[0:1]
	global_load_dword v187, v[190:191], off
	ds_read_b32 v36, v4
	s_waitcnt vmcnt(31) lgkmcnt(0)
	v_mul_f32_e32 v36, v156, v36
	ds_write_b32 v34, v36
	ds_read_b32 v37, v4 offset:256
	ds_read_b32 v73, v4 offset:8
	v_cvt_pk_bf16_f32 v36, v36, 0
	v_lshlrev_b32_e32 v36, 16, v36
	s_waitcnt lgkmcnt(1)
	v_mul_f32_e32 v37, v156, v37
	s_waitcnt vmcnt(30) lgkmcnt(0)
	v_mul_f32_e32 v35, v157, v73
	ds_write_b32 v34, v35 offset:264
	v_pk_add_f32 v[12:13], v[12:13], v[36:37]
	ds_read_b32 v37, v4 offset:264
	ds_read_b32 v73, v4 offset:16
	v_cvt_pk_bf16_f32 v35, v35, 0
	v_lshlrev_b32_e32 v36, 16, v35
	s_waitcnt lgkmcnt(1)
	v_mul_f32_e32 v37, v157, v37
	s_waitcnt vmcnt(29) lgkmcnt(0)
	v_mul_f32_e32 v35, v158, v73
	ds_write_b32 v34, v35 offset:528
	v_pk_add_f32 v[12:13], v[12:13], v[36:37]
	ds_read_b32 v37, v4 offset:272
	ds_read_b32 v66, v4 offset:24
	v_cvt_pk_bf16_f32 v35, v35, 0
	v_lshlrev_b32_e32 v36, 16, v35
	s_waitcnt lgkmcnt(1)
	v_mul_f32_e32 v37, v158, v37
	s_waitcnt vmcnt(28) lgkmcnt(0)
	v_mul_f32_e32 v35, v159, v66
	ds_write_b32 v34, v35 offset:792
	v_pk_add_f32 v[12:13], v[12:13], v[36:37]
	ds_read_b32 v37, v4 offset:280
	ds_read_b32 v66, v4 offset:32
	v_cvt_pk_bf16_f32 v35, v35, 0
	v_lshlrev_b32_e32 v36, 16, v35
	s_waitcnt lgkmcnt(1)
	v_mul_f32_e32 v37, v159, v37
	s_waitcnt vmcnt(27) lgkmcnt(0)
	v_mul_f32_e32 v35, v160, v66
	ds_write_b32 v34, v35 offset:1056
	v_pk_add_f32 v[12:13], v[12:13], v[36:37]
	ds_read_b32 v37, v4 offset:288
	ds_read_b32 v66, v4 offset:40
	v_cvt_pk_bf16_f32 v35, v35, 0
	v_lshlrev_b32_e32 v36, 16, v35
	s_waitcnt lgkmcnt(1)
	v_mul_f32_e32 v37, v160, v37
	s_waitcnt vmcnt(26) lgkmcnt(0)
	v_mul_f32_e32 v35, v161, v66
	ds_write_b32 v34, v35 offset:1320
	v_pk_add_f32 v[12:13], v[12:13], v[36:37]
	ds_read_b32 v37, v4 offset:296
	ds_read_b32 v66, v4 offset:48
	v_cvt_pk_bf16_f32 v35, v35, 0
	v_lshlrev_b32_e32 v36, 16, v35
	s_waitcnt lgkmcnt(1)
	v_mul_f32_e32 v37, v161, v37
	s_waitcnt vmcnt(25) lgkmcnt(0)
	v_mul_f32_e32 v35, v162, v66
	ds_write_b32 v34, v35 offset:1584
	v_pk_add_f32 v[12:13], v[12:13], v[36:37]
	ds_read_b32 v37, v4 offset:304
	ds_read_b32 v66, v4 offset:56
	v_cvt_pk_bf16_f32 v35, v35, 0
	v_lshlrev_b32_e32 v36, 16, v35
	s_waitcnt lgkmcnt(1)
	v_mul_f32_e32 v37, v162, v37
	s_waitcnt vmcnt(24) lgkmcnt(0)
	v_mul_f32_e32 v35, v163, v66
	ds_write_b32 v34, v35 offset:1848
	v_pk_add_f32 v[12:13], v[12:13], v[36:37]
	ds_read_b32 v37, v4 offset:312
	v_cvt_pk_bf16_f32 v35, v35, 0
	v_lshlrev_b32_e32 v36, 16, v35
	v_add_u32_e32 v34, 0x840, v34
	v_add_u32_e32 v4, 64, v4
	s_waitcnt lgkmcnt(0)
	v_mul_f32_e32 v37, v163, v37
	v_pk_add_f32 v[12:13], v[12:13], v[36:37]
	ds_read_b32 v36, v4
	s_waitcnt vmcnt(23) lgkmcnt(0)
; __device__ __forceinline__ unsigned cvtpk(float lo, float hi) { f32x2_t v = {lo, hi}; bf16x2_t b = __builtin_convertvector(v, bf16x2_t); return __builtin_bit_cast(unsigned, b); }
; __device__ __forceinline__ float bf2f(unsigned b) { return __uint_as_float(b << 16); }
; __device__ __forceinline__ void transpose_item_ln(const float* W, int K, int N, bf16* WT, int mode, LAS float* scr, int item, int lane, const float* gk, const float* bk, float* part) {
;     ...
; #pragma unroll 8
;     for (int i = 0; i < 32; ++i) { const int kk = 2 * i + (lane >> 5); const float w = W[(size_t)(k0 + kk) * N + nsrc]; const float wg = w * gs[kk];
;         scr[kk * 33 + (lane & 31)] = wg; s1 += bf2f(cvtpk(wg, 0.f) & 0xffffu); s2 += bs[kk] * w; }
	v_mul_f32_e32 v36, v164, v36
	ds_write_b32 v34, v36
	ds_read_b32 v37, v4 offset:256
	ds_read_b32 v73, v4 offset:8
	v_cvt_pk_bf16_f32 v36, v36, 0
	v_lshlrev_b32_e32 v36, 16, v36
	s_waitcnt lgkmcnt(1)
	v_mul_f32_e32 v37, v164, v37
	s_waitcnt vmcnt(22) lgkmcnt(0)
	v_mul_f32_e32 v35, v165, v73
	ds_write_b32 v34, v35 offset:264
	v_pk_add_f32 v[12:13], v[12:13], v[36:37]
	ds_read_b32 v37, v4 offset:264
	ds_read_b32 v73, v4 offset:16
	v_cvt_pk_bf16_f32 v35, v35, 0
	v_lshlrev_b32_e32 v36, 16, v35
	s_waitcnt lgkmcnt(1)
	v_mul_f32_e32 v37, v165, v37
	s_waitcnt vmcnt(21) lgkmcnt(0)
	v_mul_f32_e32 v35, v166, v73
	ds_write_b32 v34, v35 offset:528
	v_pk_add_f32 v[12:13], v[12:13], v[36:37]
	ds_read_b32 v37, v4 offset:272
	ds_read_b32 v66, v4 offset:24
	v_cvt_pk_bf16_f32 v35, v35, 0
	v_lshlrev_b32_e32 v36, 16, v35
	s_waitcnt lgkmcnt(1)
	v_mul_f32_e32 v37, v166, v37
	s_waitcnt vmcnt(20) lgkmcnt(0)
	v_mul_f32_e32 v35, v167, v66
	ds_write_b32 v34, v35 offset:792
	v_pk_add_f32 v[12:13], v[12:13], v[36:37]
	ds_read_b32 v37, v4 offset:280
	ds_read_b32 v66, v4 offset:32
	v_cvt_pk_bf16_f32 v35, v35, 0
	v_lshlrev_b32_e32 v36, 16, v35
	s_waitcnt lgkmcnt(1)
	v_mul_f32_e32 v37, v167, v37
	s_waitcnt vmcnt(19) lgkmcnt(0)
	v_mul_f32_e32 v35, v168, v66
	ds_write_b32 v34, v35 offset:1056
	v_pk_add_f32 v[12:13], v[12:13], v[36:37]
	ds_read_b32 v37, v4 offset:288
	ds_read_b32 v66, v4 offset:40
	v_cvt_pk_bf16_f32 v35, v35, 0
	v_lshlrev_b32_e32 v36, 16, v35
	s_waitcnt lgkmcnt(1)
	v_mul_f32_e32 v37, v168, v37
	s_waitcnt vmcnt(18) lgkmcnt(0)
	v_mul_f32_e32 v35, v169, v66
	ds_write_b32 v34, v35 offset:1320
	v_pk_add_f32 v[12:13], v[12:13], v[36:37]
	ds_read_b32 v37, v4 offset:296
	ds_read_b32 v66, v4 offset:48
	v_cvt_pk_bf16_f32 v35, v35, 0
	v_lshlrev_b32_e32 v36, 16, v35
	s_waitcnt lgkmcnt(1)
	v_mul_f32_e32 v37, v169, v37
	s_waitcnt vmcnt(17) lgkmcnt(0)
	v_mul_f32_e32 v35, v170, v66
	ds_write_b32 v34, v35 offset:1584
	v_pk_add_f32 v[12:13], v[12:13], v[36:37]
	ds_read_b32 v37, v4 offset:304
	ds_read_b32 v66, v4 offset:56
	v_cvt_pk_bf16_f32 v35, v35, 0
	v_lshlrev_b32_e32 v36, 16, v35
	s_waitcnt lgkmcnt(1)
	v_mul_f32_e32 v37, v170, v37
	s_waitcnt vmcnt(16) lgkmcnt(0)
	v_mul_f32_e32 v35, v171, v66
	ds_write_b32 v34, v35 offset:1848
	v_pk_add_f32 v[12:13], v[12:13], v[36:37]
	ds_read_b32 v37, v4 offset:312
	v_cvt_pk_bf16_f32 v35, v35, 0
	v_lshlrev_b32_e32 v36, 16, v35
	v_add_u32_e32 v34, 0x840, v34
	v_add_u32_e32 v4, 64, v4
	s_waitcnt lgkmcnt(0)
	v_mul_f32_e32 v37, v171, v37
	v_pk_add_f32 v[12:13], v[12:13], v[36:37]
	ds_read_b32 v36, v4
	s_waitcnt vmcnt(15) lgkmcnt(0)
	v_mul_f32_e32 v36, v172, v36
	ds_write_b32 v34, v36
	ds_read_b32 v37, v4 offset:256
	ds_read_b32 v73, v4 offset:8
	v_cvt_pk_bf16_f32 v36, v36, 0
	v_lshlrev_b32_e32 v36, 16, v36
	s_waitcnt lgkmcnt(1)
	v_mul_f32_e32 v37, v172, v37
	s_waitcnt vmcnt(14) lgkmcnt(0)
	v_mul_f32_e32 v35, v173, v73
	ds_write_b32 v34, v35 offset:264
	v_pk_add_f32 v[12:13], v[12:13], v[36:37]
	ds_read_b32 v37, v4 offset:264
	ds_read_b32 v73, v4 offset:16
	v_cvt_pk_bf16_f32 v35, v35, 0
	v_lshlrev_b32_e32 v36, 16, v35
	s_waitcnt lgkmcnt(1)
	v_mul_f32_e32 v37, v173, v37
	s_waitcnt vmcnt(13) lgkmcnt(0)
	v_mul_f32_e32 v35, v174, v73
	ds_write_b32 v34, v35 offset:528
	v_pk_add_f32 v[12:13], v[12:13], v[36:37]
	ds_read_b32 v37, v4 offset:272
	ds_read_b32 v66, v4 offset:24
	v_cvt_pk_bf16_f32 v35, v35, 0
	v_lshlrev_b32_e32 v36, 16, v35
	s_waitcnt lgkmcnt(1)
	v_mul_f32_e32 v37, v174, v37
	s_waitcnt vmcnt(12) lgkmcnt(0)
	v_mul_f32_e32 v35, v175, v66
	ds_write_b32 v34, v35 offset:792
	v_pk_add_f32 v[12:13], v[12:13], v[36:37]
	ds_read_b32 v37, v4 offset:280
	ds_read_b32 v66, v4 offset:32
	v_cvt_pk_bf16_f32 v35, v35, 0
	v_lshlrev_b32_e32 v36, 16, v35
	s_waitcnt lgkmcnt(1)
	v_mul_f32_e32 v37, v175, v37
	s_waitcnt vmcnt(11) lgkmcnt(0)
	v_mul_f32_e32 v35, v176, v66
	ds_write_b32 v34, v35 offset:1056
	v_pk_add_f32 v[12:13], v[12:13], v[36:37]
	ds_read_b32 v37, v4 offset:288
	ds_read_b32 v66, v4 offset:40
	v_cvt_pk_bf16_f32 v35, v35, 0
	v_lshlrev_b32_e32 v36, 16, v35
	s_waitcnt lgkmcnt(1)
	v_mul_f32_e32 v37, v176, v37
	s_waitcnt vmcnt(10) lgkmcnt(0)
; __device__ __forceinline__ unsigned cvtpk(float lo, float hi) { f32x2_t v = {lo, hi}; bf16x2_t b = __builtin_convertvector(v, bf16x2_t); return __builtin_bit_cast(unsigned, b); }
; __device__ __forceinline__ float bf2f(unsigned b) { return __uint_as_float(b << 16); }
; __device__ __forceinline__ void transpose_item_ln(const float* W, int K, int N, bf16* WT, int mode, LAS float* scr, int item, int lane, const float* gk, const float* bk, float* part) {
;     ...
; #pragma unroll 8
;     for (int i = 0; i < 32; ++i) { const int kk = 2 * i + (lane >> 5); const float w = W[(size_t)(k0 + kk) * N + nsrc]; const float wg = w * gs[kk];
;         scr[kk * 33 + (lane & 31)] = wg; s1 += bf2f(cvtpk(wg, 0.f) & 0xffffu); s2 += bs[kk] * w; }
;     s1 += __shfl_xor(s1, 32); s2 += __shfl_xor(s2, 32);
;     if (lane < 32) { float* pp = part + ((size_t)kb * NC12 + n0 + lane) * 2; pp[0] = s1; pp[1] = s2; }
	v_mul_f32_e32 v35, v177, v66
	ds_write_b32 v34, v35 offset:1320
	v_pk_add_f32 v[12:13], v[12:13], v[36:37]
	ds_read_b32 v37, v4 offset:296
	ds_read_b32 v66, v4 offset:48
	v_cvt_pk_bf16_f32 v35, v35, 0
	v_lshlrev_b32_e32 v36, 16, v35
	s_waitcnt lgkmcnt(1)
	v_mul_f32_e32 v37, v177, v37
	s_waitcnt vmcnt(9) lgkmcnt(0)
	v_mul_f32_e32 v35, v178, v66
	ds_write_b32 v34, v35 offset:1584
	v_pk_add_f32 v[12:13], v[12:13], v[36:37]
	ds_read_b32 v37, v4 offset:304
	ds_read_b32 v66, v4 offset:56
	v_cvt_pk_bf16_f32 v35, v35, 0
	v_lshlrev_b32_e32 v36, 16, v35
	s_waitcnt lgkmcnt(1)
	v_mul_f32_e32 v37, v178, v37
	s_waitcnt vmcnt(8) lgkmcnt(0)
	v_mul_f32_e32 v35, v179, v66
	ds_write_b32 v34, v35 offset:1848
	v_pk_add_f32 v[12:13], v[12:13], v[36:37]
	ds_read_b32 v37, v4 offset:312
	v_cvt_pk_bf16_f32 v35, v35, 0
	v_lshlrev_b32_e32 v36, 16, v35
	v_add_u32_e32 v34, 0x840, v34
	v_add_u32_e32 v4, 64, v4
	s_waitcnt lgkmcnt(0)
	v_mul_f32_e32 v37, v179, v37
	v_pk_add_f32 v[12:13], v[12:13], v[36:37]
	ds_read_b32 v36, v4
	s_waitcnt vmcnt(7) lgkmcnt(0)
	v_mul_f32_e32 v36, v180, v36
	ds_write_b32 v34, v36
	ds_read_b32 v37, v4 offset:256
	ds_read_b32 v73, v4 offset:8
	v_cvt_pk_bf16_f32 v36, v36, 0
	v_lshlrev_b32_e32 v36, 16, v36
	s_waitcnt lgkmcnt(1)
	v_mul_f32_e32 v37, v180, v37
	s_waitcnt vmcnt(6) lgkmcnt(0)
	v_mul_f32_e32 v35, v181, v73
	ds_write_b32 v34, v35 offset:264
	v_pk_add_f32 v[12:13], v[12:13], v[36:37]
	ds_read_b32 v37, v4 offset:264
	ds_read_b32 v73, v4 offset:16
	v_cvt_pk_bf16_f32 v35, v35, 0
	v_lshlrev_b32_e32 v36, 16, v35
	s_waitcnt lgkmcnt(1)
	v_mul_f32_e32 v37, v181, v37
	s_waitcnt vmcnt(5) lgkmcnt(0)
	v_mul_f32_e32 v35, v182, v73
	ds_write_b32 v34, v35 offset:528
	v_pk_add_f32 v[12:13], v[12:13], v[36:37]
	ds_read_b32 v37, v4 offset:272
	ds_read_b32 v66, v4 offset:24
	v_cvt_pk_bf16_f32 v35, v35, 0
	v_lshlrev_b32_e32 v36, 16, v35
	s_waitcnt lgkmcnt(1)
	v_mul_f32_e32 v37, v182, v37
	s_waitcnt vmcnt(4) lgkmcnt(0)
	v_mul_f32_e32 v35, v183, v66
	ds_write_b32 v34, v35 offset:792
	v_pk_add_f32 v[12:13], v[12:13], v[36:37]
	ds_read_b32 v37, v4 offset:280
	ds_read_b32 v66, v4 offset:32
	v_cvt_pk_bf16_f32 v35, v35, 0
	v_lshlrev_b32_e32 v36, 16, v35
	s_waitcnt lgkmcnt(1)
	v_mul_f32_e32 v37, v183, v37
	s_waitcnt vmcnt(3) lgkmcnt(0)
	v_mul_f32_e32 v35, v184, v66
	ds_write_b32 v34, v35 offset:1056
	v_pk_add_f32 v[12:13], v[12:13], v[36:37]
	ds_read_b32 v37, v4 offset:288
	ds_read_b32 v66, v4 offset:40
	v_cvt_pk_bf16_f32 v35, v35, 0
	v_lshlrev_b32_e32 v36, 16, v35
	s_waitcnt lgkmcnt(1)
	v_mul_f32_e32 v37, v184, v37
	s_waitcnt vmcnt(2) lgkmcnt(0)
	v_mul_f32_e32 v35, v185, v66
	ds_write_b32 v34, v35 offset:1320
	v_pk_add_f32 v[12:13], v[12:13], v[36:37]
	ds_read_b32 v37, v4 offset:296
	ds_read_b32 v66, v4 offset:48
	v_cvt_pk_bf16_f32 v35, v35, 0
	v_lshlrev_b32_e32 v36, 16, v35
	s_waitcnt lgkmcnt(1)
	v_mul_f32_e32 v37, v185, v37
	s_waitcnt vmcnt(1) lgkmcnt(0)
	v_mul_f32_e32 v35, v186, v66
	ds_write_b32 v34, v35 offset:1584
	v_pk_add_f32 v[12:13], v[12:13], v[36:37]
	ds_read_b32 v37, v4 offset:304
	ds_read_b32 v66, v4 offset:56
	v_cvt_pk_bf16_f32 v35, v35, 0
	v_lshlrev_b32_e32 v36, 16, v35
	s_waitcnt lgkmcnt(1)
	v_mul_f32_e32 v37, v186, v37
	s_waitcnt vmcnt(0) lgkmcnt(0)
	v_mul_f32_e32 v35, v187, v66
	ds_write_b32 v34, v35 offset:1848
	v_pk_add_f32 v[12:13], v[12:13], v[36:37]
	ds_read_b32 v37, v4 offset:312
	v_cvt_pk_bf16_f32 v35, v35, 0
	v_lshlrev_b32_e32 v36, 16, v35
	v_add_u32_e32 v34, 0x840, v34
	v_add_u32_e32 v4, 64, v4
	s_waitcnt lgkmcnt(0)
	v_mul_f32_e32 v37, v187, v37
	v_pk_add_f32 v[12:13], v[12:13], v[36:37]
	ds_bpermute_b32 v14, v48, v12
	ds_bpermute_b32 v15, v48, v13
	s_and_saveexec_b64 s[0:1], vcc
	s_cbranch_execz .LBB0_40
	v_mul_u32_u24_sdwa v4, v9, s48 dst_sel:DWORD dst_unused:UNUSED_PAD src0_sel:WORD_0 src1_sel:DWORD
	v_add_u32_e32 v4, v4, v11
	v_mul_hi_i32_i24_e32 v19, 0x148000, v10
	v_mul_i32_i24_e32 v18, 0x148000, v10
	v_or_b32_e32 v4, v4, v16
	v_lshl_add_u64 v[18:19], s[12:13], 0, v[18:19]
	v_lshlrev_b32_e32 v4, 3, v4
	v_lshl_add_u64 v[18:19], v[18:19], 0, v[4:5]
	s_waitcnt lgkmcnt(0)
	v_pk_add_f32 v[12:13], v[12:13], v[14:15]
	global_store_dwordx2 v[18:19], v[12:13], off

; __device__ __forceinline__ unsigned cvtpk(float lo, float hi) { f32x2_t v = {lo, hi}; bf16x2_t b = __builtin_convertvector(v, bf16x2_t); return __builtin_bit_cast(unsigned, b); }
; __device__ __forceinline__ float bf2f(unsigned b) { return __uint_as_float(b << 16); }
; __device__ __forceinline__ void transpose_item_ln(const float* W, int K, int N, bf16* WT, int mode, LAS float* scr, int item, int lane, const float* gk, const float* bk, float* part) {
;     ...
;     float s1 = 0.f, s2 = 0.f;
; #pragma unroll 8
;     for (int i = 0; i < 32; ++i) { const int kk = 2 * i + (lane >> 5); const float w = W[(size_t)(k0 + kk) * N + nsrc]; const float wg = w * gs[kk];
;         scr[kk * 33 + (lane & 31)] = wg; s1 += bf2f(cvtpk(wg, 0.f) & 0xffffu); s2 += bs[kk] * w; }
;     s1 += __shfl_xor(s1, 32); s2 += __shfl_xor(s2, 32);
;     if (lane < 32) { float* pp = part + ((size_t)kb * NC12 + n0 + lane) * 2; pp[0] = s1; pp[1] = s2; }
.LBB0_60:
	v_lshl_add_u64 v[188:189], v[36:37], 0, s[0:1]
	global_load_dword v156, v[188:189], off
	v_lshl_add_u64 v[190:191], v[34:35], 0, s[0:1]
	global_load_dword v157, v[190:191], off
	v_lshl_add_u64 v[188:189], v[30:31], 0, s[0:1]
	global_load_dword v158, v[188:189], off
	v_lshl_add_u64 v[190:191], v[28:29], 0, s[0:1]
	global_load_dword v159, v[190:191], off
	v_lshl_add_u64 v[188:189], v[26:27], 0, s[0:1]
	global_load_dword v160, v[188:189], off
	v_lshl_add_u64 v[190:191], v[24:25], 0, s[0:1]
	global_load_dword v161, v[190:191], off
	v_lshl_add_u64 v[188:189], v[22:23], 0, s[0:1]
	global_load_dword v162, v[188:189], off
	v_lshl_add_u64 v[190:191], v[20:21], 0, s[0:1]
	global_load_dword v163, v[190:191], off
	s_add_u32 s0, s0, 0x4c000
	s_addc_u32 s1, s1, 0
	v_lshl_add_u64 v[188:189], v[36:37], 0, s[0:1]
	global_load_dword v164, v[188:189], off
	v_lshl_add_u64 v[190:191], v[34:35], 0, s[0:1]
	global_load_dword v165, v[190:191], off
	v_lshl_add_u64 v[188:189], v[30:31], 0, s[0:1]
	global_load_dword v166, v[188:189], off
	v_lshl_add_u64 v[190:191], v[28:29], 0, s[0:1]
	global_load_dword v167, v[190:191], off
	v_lshl_add_u64 v[188:189], v[26:27], 0, s[0:1]
	global_load_dword v168, v[188:189], off
	v_lshl_add_u64 v[190:191], v[24:25], 0, s[0:1]
	global_load_dword v169, v[190:191], off
	v_lshl_add_u64 v[188:189], v[22:23], 0, s[0:1]
	global_load_dword v170, v[188:189], off
	v_lshl_add_u64 v[190:191], v[20:21], 0, s[0:1]
	global_load_dword v171, v[190:191], off
	s_add_u32 s0, s0, 0x4c000
	s_addc_u32 s1, s1, 0
	v_lshl_add_u64 v[188:189], v[36:37], 0, s[0:1]
	global_load_dword v172, v[188:189], off
	v_lshl_add_u64 v[190:191], v[34:35], 0, s[0:1]
	global_load_dword v173, v[190:191], off
	v_lshl_add_u64 v[188:189], v[30:31], 0, s[0:1]
	global_load_dword v174, v[188:189], off
	v_lshl_add_u64 v[190:191], v[28:29], 0, s[0:1]
	global_load_dword v175, v[190:191], off
	v_lshl_add_u64 v[188:189], v[26:27], 0, s[0:1]
	global_load_dword v176, v[188:189], off
	v_lshl_add_u64 v[190:191], v[24:25], 0, s[0:1]
	global_load_dword v177, v[190:191], off
	v_lshl_add_u64 v[188:189], v[22:23], 0, s[0:1]
	global_load_dword v178, v[188:189], off
	v_lshl_add_u64 v[190:191], v[20:21], 0, s[0:1]
	global_load_dword v179, v[190:191], off
	s_add_u32 s0, s0, 0x4c000
	s_addc_u32 s1, s1, 0
	v_lshl_add_u64 v[188:189], v[36:37], 0, s[0:1]
	global_load_dword v180, v[188:189], off
	v_lshl_add_u64 v[190:191], v[34:35], 0, s[0:1]
	global_load_dword v181, v[190:191], off
	v_lshl_add_u64 v[188:189], v[30:31], 0, s[0:1]
	global_load_dword v182, v[188:189], off
	v_lshl_add_u64 v[190:191], v[28:29], 0, s[0:1]
	global_load_dword v183, v[190:191], off
	v_lshl_add_u64 v[188:189], v[26:27], 0, s[0:1]
	global_load_dword v184, v[188:189], off
	v_lshl_add_u64 v[190:191], v[24:25], 0, s[0:1]
	global_load_dword v185, v[190:191], off
	v_lshl_add_u64 v[188:189], v[22:23], 0, s[0:1]
	global_load_dword v186, v[188:189], off
	v_lshl_add_u64 v[190:191], v[20:21], 0, s[0:1]
	global_load_dword v187, v[190:191], off
	ds_read_b32 v66, v3
	s_waitcnt vmcnt(31) lgkmcnt(0)
	v_mul_f32_e32 v66, v156, v66
	ds_write_b32 v9, v66
	ds_read_b32 v67, v3 offset:256
	ds_read_b32 v73, v3 offset:8
	v_cvt_pk_bf16_f32 v66, v66, 0
	v_lshlrev_b32_e32 v66, 16, v66
	s_waitcnt lgkmcnt(1)
	v_mul_f32_e32 v67, v156, v67
	s_waitcnt vmcnt(30) lgkmcnt(0)
	v_mul_f32_e32 v11, v157, v73
	ds_write_b32 v9, v11 offset:264
	v_pk_add_f32 v[18:19], v[18:19], v[66:67]
	ds_read_b32 v67, v3 offset:264
	ds_read_b32 v73, v3 offset:16
	v_cvt_pk_bf16_f32 v11, v11, 0
	v_lshlrev_b32_e32 v66, 16, v11
	s_waitcnt lgkmcnt(1)
	v_mul_f32_e32 v67, v157, v67
	s_waitcnt vmcnt(29) lgkmcnt(0)
	v_mul_f32_e32 v11, v158, v73
	ds_write_b32 v9, v11 offset:528
	ds_read_b32 v13, v3 offset:272
	ds_read_b32 v73, v3 offset:24
	v_cvt_pk_bf16_f32 v11, v11, 0
	v_pk_add_f32 v[18:19], v[18:19], v[66:67]
	v_lshlrev_b32_e32 v66, 16, v11
	s_waitcnt lgkmcnt(1)
	v_mul_f32_e32 v67, v158, v13
	s_waitcnt vmcnt(28) lgkmcnt(0)
	v_mul_f32_e32 v11, v159, v73
	ds_write_b32 v9, v11 offset:792
	ds_read_b32 v13, v3 offset:280
	ds_read_b32 v15, v3 offset:32
	v_cvt_pk_bf16_f32 v11, v11, 0
	v_pk_add_f32 v[18:19], v[18:19], v[66:67]
	v_lshlrev_b32_e32 v66, 16, v11
	s_waitcnt lgkmcnt(1)
	v_mul_f32_e32 v67, v159, v13
	s_waitcnt vmcnt(27) lgkmcnt(0)
	v_mul_f32_e32 v11, v160, v15
	ds_write_b32 v9, v11 offset:1056
	ds_read_b32 v13, v3 offset:288
	ds_read_b32 v15, v3 offset:40
	v_cvt_pk_bf16_f32 v11, v11, 0
	v_pk_add_f32 v[18:19], v[18:19], v[66:67]
	v_lshlrev_b32_e32 v66, 16, v11
	s_waitcnt lgkmcnt(1)
	v_mul_f32_e32 v67, v160, v13
	s_waitcnt vmcnt(26) lgkmcnt(0)
	v_mul_f32_e32 v11, v161, v15
	ds_write_b32 v9, v11 offset:1320
	ds_read_b32 v13, v3 offset:296
	ds_read_b32 v15, v3 offset:48
	v_cvt_pk_bf16_f32 v11, v11, 0
	v_pk_add_f32 v[18:19], v[18:19], v[66:67]
	v_lshlrev_b32_e32 v66, 16, v11
	s_waitcnt lgkmcnt(1)
	v_mul_f32_e32 v67, v161, v13
	s_waitcnt vmcnt(25) lgkmcnt(0)
	v_mul_f32_e32 v11, v162, v15
	ds_write_b32 v9, v11 offset:1584
	ds_read_b32 v13, v3 offset:304
	ds_read_b32 v15, v3 offset:56
	v_cvt_pk_bf16_f32 v11, v11, 0
	v_pk_add_f32 v[18:19], v[18:19], v[66:67]
	v_lshlrev_b32_e32 v66, 16, v11
	s_waitcnt lgkmcnt(1)
	v_mul_f32_e32 v67, v162, v13
	s_waitcnt vmcnt(24) lgkmcnt(0)
	v_mul_f32_e32 v11, v163, v15
	ds_write_b32 v9, v11 offset:1848
	ds_read_b32 v13, v3 offset:312
	v_cvt_pk_bf16_f32 v11, v11, 0
	v_pk_add_f32 v[18:19], v[18:19], v[66:67]
	v_lshlrev_b32_e32 v66, 16, v11
	v_add_u32_e32 v9, 0x840, v9
	s_waitcnt lgkmcnt(0)
	v_mul_f32_e32 v67, v163, v13
	v_add_u32_e32 v3, 64, v3
	v_pk_add_f32 v[18:19], v[18:19], v[66:67]
	ds_read_b32 v66, v3
	s_waitcnt vmcnt(23) lgkmcnt(0)
; __device__ __forceinline__ unsigned cvtpk(float lo, float hi) { f32x2_t v = {lo, hi}; bf16x2_t b = __builtin_convertvector(v, bf16x2_t); return __builtin_bit_cast(unsigned, b); }
; __device__ __forceinline__ float bf2f(unsigned b) { return __uint_as_float(b << 16); }
; __device__ __forceinline__ void transpose_item_ln(const float* W, int K, int N, bf16* WT, int mode, LAS float* scr, int item, int lane, const float* gk, const float* bk, float* part) {
;     ...
; #pragma unroll 8
;     for (int i = 0; i < 32; ++i) { const int kk = 2 * i + (lane >> 5); const float w = W[(size_t)(k0 + kk) * N + nsrc]; const float wg = w * gs[kk];
;         scr[kk * 33 + (lane & 31)] = wg; s1 += bf2f(cvtpk(wg, 0.f) & 0xffffu); s2 += bs[kk] * w; }
	v_mul_f32_e32 v66, v164, v66
	ds_write_b32 v9, v66
	ds_read_b32 v67, v3 offset:256
	ds_read_b32 v73, v3 offset:8
	v_cvt_pk_bf16_f32 v66, v66, 0
	v_lshlrev_b32_e32 v66, 16, v66
	s_waitcnt lgkmcnt(1)
	v_mul_f32_e32 v67, v164, v67
	s_waitcnt vmcnt(22) lgkmcnt(0)
	v_mul_f32_e32 v11, v165, v73
	ds_write_b32 v9, v11 offset:264
	v_pk_add_f32 v[18:19], v[18:19], v[66:67]
	ds_read_b32 v67, v3 offset:264
	ds_read_b32 v73, v3 offset:16
	v_cvt_pk_bf16_f32 v11, v11, 0
	v_lshlrev_b32_e32 v66, 16, v11
	s_waitcnt lgkmcnt(1)
	v_mul_f32_e32 v67, v165, v67
	s_waitcnt vmcnt(21) lgkmcnt(0)
	v_mul_f32_e32 v11, v166, v73
	ds_write_b32 v9, v11 offset:528
	ds_read_b32 v13, v3 offset:272
	ds_read_b32 v73, v3 offset:24
	v_cvt_pk_bf16_f32 v11, v11, 0
	v_pk_add_f32 v[18:19], v[18:19], v[66:67]
	v_lshlrev_b32_e32 v66, 16, v11
	s_waitcnt lgkmcnt(1)
	v_mul_f32_e32 v67, v166, v13
	s_waitcnt vmcnt(20) lgkmcnt(0)
	v_mul_f32_e32 v11, v167, v73
	ds_write_b32 v9, v11 offset:792
	ds_read_b32 v13, v3 offset:280
	ds_read_b32 v15, v3 offset:32
	v_cvt_pk_bf16_f32 v11, v11, 0
	v_pk_add_f32 v[18:19], v[18:19], v[66:67]
	v_lshlrev_b32_e32 v66, 16, v11
	s_waitcnt lgkmcnt(1)
	v_mul_f32_e32 v67, v167, v13
	s_waitcnt vmcnt(19) lgkmcnt(0)
	v_mul_f32_e32 v11, v168, v15
	ds_write_b32 v9, v11 offset:1056
	ds_read_b32 v13, v3 offset:288
	ds_read_b32 v15, v3 offset:40
	v_cvt_pk_bf16_f32 v11, v11, 0
	v_pk_add_f32 v[18:19], v[18:19], v[66:67]
	v_lshlrev_b32_e32 v66, 16, v11
	s_waitcnt lgkmcnt(1)
	v_mul_f32_e32 v67, v168, v13
	s_waitcnt vmcnt(18) lgkmcnt(0)
	v_mul_f32_e32 v11, v169, v15
	ds_write_b32 v9, v11 offset:1320
	ds_read_b32 v13, v3 offset:296
	ds_read_b32 v15, v3 offset:48
	v_cvt_pk_bf16_f32 v11, v11, 0
	v_pk_add_f32 v[18:19], v[18:19], v[66:67]
	v_lshlrev_b32_e32 v66, 16, v11
	s_waitcnt lgkmcnt(1)
	v_mul_f32_e32 v67, v169, v13
	s_waitcnt vmcnt(17) lgkmcnt(0)
	v_mul_f32_e32 v11, v170, v15
	ds_write_b32 v9, v11 offset:1584
	ds_read_b32 v13, v3 offset:304
	ds_read_b32 v15, v3 offset:56
	v_cvt_pk_bf16_f32 v11, v11, 0
	v_pk_add_f32 v[18:19], v[18:19], v[66:67]
	v_lshlrev_b32_e32 v66, 16, v11
	s_waitcnt lgkmcnt(1)
	v_mul_f32_e32 v67, v170, v13
	s_waitcnt vmcnt(16) lgkmcnt(0)
	v_mul_f32_e32 v11, v171, v15
	ds_write_b32 v9, v11 offset:1848
	ds_read_b32 v13, v3 offset:312
	v_cvt_pk_bf16_f32 v11, v11, 0
	v_pk_add_f32 v[18:19], v[18:19], v[66:67]
	v_lshlrev_b32_e32 v66, 16, v11
	v_add_u32_e32 v9, 0x840, v9
	s_waitcnt lgkmcnt(0)
	v_mul_f32_e32 v67, v171, v13
	v_add_u32_e32 v3, 64, v3
	v_pk_add_f32 v[18:19], v[18:19], v[66:67]
	ds_read_b32 v66, v3
	s_waitcnt vmcnt(15) lgkmcnt(0)
	v_mul_f32_e32 v66, v172, v66
	ds_write_b32 v9, v66
	ds_read_b32 v67, v3 offset:256
	ds_read_b32 v73, v3 offset:8
	v_cvt_pk_bf16_f32 v66, v66, 0
	v_lshlrev_b32_e32 v66, 16, v66
	s_waitcnt lgkmcnt(1)
	v_mul_f32_e32 v67, v172, v67
	s_waitcnt vmcnt(14) lgkmcnt(0)
	v_mul_f32_e32 v11, v173, v73
	ds_write_b32 v9, v11 offset:264
	v_pk_add_f32 v[18:19], v[18:19], v[66:67]
	ds_read_b32 v67, v3 offset:264
	ds_read_b32 v73, v3 offset:16
	v_cvt_pk_bf16_f32 v11, v11, 0
	v_lshlrev_b32_e32 v66, 16, v11
	s_waitcnt lgkmcnt(1)
	v_mul_f32_e32 v67, v173, v67
	s_waitcnt vmcnt(13) lgkmcnt(0)
	v_mul_f32_e32 v11, v174, v73
	ds_write_b32 v9, v11 offset:528
	ds_read_b32 v13, v3 offset:272
	ds_read_b32 v73, v3 offset:24
	v_cvt_pk_bf16_f32 v11, v11, 0
	v_pk_add_f32 v[18:19], v[18:19], v[66:67]
	v_lshlrev_b32_e32 v66, 16, v11
	s_waitcnt lgkmcnt(1)
	v_mul_f32_e32 v67, v174, v13
	s_waitcnt vmcnt(12) lgkmcnt(0)
	v_mul_f32_e32 v11, v175, v73
	ds_write_b32 v9, v11 offset:792
	ds_read_b32 v13, v3 offset:280
	ds_read_b32 v15, v3 offset:32
	v_cvt_pk_bf16_f32 v11, v11, 0
	v_pk_add_f32 v[18:19], v[18:19], v[66:67]
	v_lshlrev_b32_e32 v66, 16, v11
	s_waitcnt lgkmcnt(1)
	v_mul_f32_e32 v67, v175, v13
	s_waitcnt vmcnt(11) lgkmcnt(0)
	v_mul_f32_e32 v11, v176, v15
	ds_write_b32 v9, v11 offset:1056
	ds_read_b32 v13, v3 offset:288
	ds_read_b32 v15, v3 offset:40
	v_cvt_pk_bf16_f32 v11, v11, 0
	v_pk_add_f32 v[18:19], v[18:19], v[66:67]
	v_lshlrev_b32_e32 v66, 16, v11
	s_waitcnt lgkmcnt(1)
	v_mul_f32_e32 v67, v176, v13
	s_waitcnt vmcnt(10) lgkmcnt(0)
; __device__ __forceinline__ unsigned cvtpk(float lo, float hi) { f32x2_t v = {lo, hi}; bf16x2_t b = __builtin_convertvector(v, bf16x2_t); return __builtin_bit_cast(unsigned, b); }
; __device__ __forceinline__ float bf2f(unsigned b) { return __uint_as_float(b << 16); }
; __device__ __forceinline__ void transpose_item_ln(const float* W, int K, int N, bf16* WT, int mode, LAS float* scr, int item, int lane, const float* gk, const float* bk, float* part) {
;     ...
; #pragma unroll 8
;     for (int i = 0; i < 32; ++i) { const int kk = 2 * i + (lane >> 5); const float w = W[(size_t)(k0 + kk) * N + nsrc]; const float wg = w * gs[kk];
;         scr[kk * 33 + (lane & 31)] = wg; s1 += bf2f(cvtpk(wg, 0.f) & 0xffffu); s2 += bs[kk] * w; }
;     s1 += __shfl_xor(s1, 32); s2 += __shfl_xor(s2, 32);
;     if (lane < 32) { float* pp = part + ((size_t)kb * NC12 + n0 + lane) * 2; pp[0] = s1; pp[1] = s2; }
	v_mul_f32_e32 v11, v177, v15
	ds_write_b32 v9, v11 offset:1320
	ds_read_b32 v13, v3 offset:296
	ds_read_b32 v15, v3 offset:48
	v_cvt_pk_bf16_f32 v11, v11, 0
	v_pk_add_f32 v[18:19], v[18:19], v[66:67]
	v_lshlrev_b32_e32 v66, 16, v11
	s_waitcnt lgkmcnt(1)
	v_mul_f32_e32 v67, v177, v13
	s_waitcnt vmcnt(9) lgkmcnt(0)
	v_mul_f32_e32 v11, v178, v15
	ds_write_b32 v9, v11 offset:1584
	ds_read_b32 v13, v3 offset:304
	ds_read_b32 v15, v3 offset:56
	v_cvt_pk_bf16_f32 v11, v11, 0
	v_pk_add_f32 v[18:19], v[18:19], v[66:67]
	v_lshlrev_b32_e32 v66, 16, v11
	s_waitcnt lgkmcnt(1)
	v_mul_f32_e32 v67, v178, v13
	s_waitcnt vmcnt(8) lgkmcnt(0)
	v_mul_f32_e32 v11, v179, v15
	ds_write_b32 v9, v11 offset:1848
	ds_read_b32 v13, v3 offset:312
	v_cvt_pk_bf16_f32 v11, v11, 0
	v_pk_add_f32 v[18:19], v[18:19], v[66:67]
	v_lshlrev_b32_e32 v66, 16, v11
	v_add_u32_e32 v9, 0x840, v9
	s_waitcnt lgkmcnt(0)
	v_mul_f32_e32 v67, v179, v13
	v_add_u32_e32 v3, 64, v3
	v_pk_add_f32 v[18:19], v[18:19], v[66:67]
	ds_read_b32 v66, v3
	s_waitcnt vmcnt(7) lgkmcnt(0)
	v_mul_f32_e32 v66, v180, v66
	ds_write_b32 v9, v66
	ds_read_b32 v67, v3 offset:256
	ds_read_b32 v73, v3 offset:8
	v_cvt_pk_bf16_f32 v66, v66, 0
	v_lshlrev_b32_e32 v66, 16, v66
	s_waitcnt lgkmcnt(1)
	v_mul_f32_e32 v67, v180, v67
	s_waitcnt vmcnt(6) lgkmcnt(0)
	v_mul_f32_e32 v11, v181, v73
	ds_write_b32 v9, v11 offset:264
	v_pk_add_f32 v[18:19], v[18:19], v[66:67]
	ds_read_b32 v67, v3 offset:264
	ds_read_b32 v73, v3 offset:16
	v_cvt_pk_bf16_f32 v11, v11, 0
	v_lshlrev_b32_e32 v66, 16, v11
	s_waitcnt lgkmcnt(1)
	v_mul_f32_e32 v67, v181, v67
	s_waitcnt vmcnt(5) lgkmcnt(0)
	v_mul_f32_e32 v11, v182, v73
	ds_write_b32 v9, v11 offset:528
	ds_read_b32 v13, v3 offset:272
	ds_read_b32 v73, v3 offset:24
	v_cvt_pk_bf16_f32 v11, v11, 0
	v_pk_add_f32 v[18:19], v[18:19], v[66:67]
	v_lshlrev_b32_e32 v66, 16, v11
	s_waitcnt lgkmcnt(1)
	v_mul_f32_e32 v67, v182, v13
	s_waitcnt vmcnt(4) lgkmcnt(0)
	v_mul_f32_e32 v11, v183, v73
	ds_write_b32 v9, v11 offset:792
	ds_read_b32 v13, v3 offset:280
	ds_read_b32 v15, v3 offset:32
	v_cvt_pk_bf16_f32 v11, v11, 0
	v_pk_add_f32 v[18:19], v[18:19], v[66:67]
	v_lshlrev_b32_e32 v66, 16, v11
	s_waitcnt lgkmcnt(1)
	v_mul_f32_e32 v67, v183, v13
	s_waitcnt vmcnt(3) lgkmcnt(0)
	v_mul_f32_e32 v11, v184, v15
	ds_write_b32 v9, v11 offset:1056
	ds_read_b32 v13, v3 offset:288
	ds_read_b32 v15, v3 offset:40
	v_cvt_pk_bf16_f32 v11, v11, 0
	v_pk_add_f32 v[18:19], v[18:19], v[66:67]
	v_lshlrev_b32_e32 v66, 16, v11
	s_waitcnt lgkmcnt(1)
	v_mul_f32_e32 v67, v184, v13
	s_waitcnt vmcnt(2) lgkmcnt(0)
	v_mul_f32_e32 v11, v185, v15
	ds_write_b32 v9, v11 offset:1320
	ds_read_b32 v13, v3 offset:296
	ds_read_b32 v15, v3 offset:48
	v_cvt_pk_bf16_f32 v11, v11, 0
	v_pk_add_f32 v[18:19], v[18:19], v[66:67]
	v_lshlrev_b32_e32 v66, 16, v11
	s_waitcnt lgkmcnt(1)
	v_mul_f32_e32 v67, v185, v13
	s_waitcnt vmcnt(1) lgkmcnt(0)
	v_mul_f32_e32 v11, v186, v15
	ds_write_b32 v9, v11 offset:1584
	ds_read_b32 v13, v3 offset:304
	ds_read_b32 v15, v3 offset:56
	v_cvt_pk_bf16_f32 v11, v11, 0
	v_pk_add_f32 v[18:19], v[18:19], v[66:67]
	v_lshlrev_b32_e32 v66, 16, v11
	s_waitcnt lgkmcnt(1)
	v_mul_f32_e32 v67, v186, v13
	s_waitcnt vmcnt(0) lgkmcnt(0)
	v_mul_f32_e32 v11, v187, v15
	ds_write_b32 v9, v11 offset:1848
	ds_read_b32 v13, v3 offset:312
	v_cvt_pk_bf16_f32 v11, v11, 0
	v_pk_add_f32 v[18:19], v[18:19], v[66:67]
	v_lshlrev_b32_e32 v66, 16, v11
	v_add_u32_e32 v9, 0x840, v9
	s_waitcnt lgkmcnt(0)
	v_mul_f32_e32 v67, v187, v13
	v_add_u32_e32 v3, 64, v3
	v_pk_add_f32 v[18:19], v[18:19], v[66:67]
	ds_bpermute_b32 v20, v48, v18
	ds_bpermute_b32 v21, v48, v19
	s_and_saveexec_b64 s[0:1], vcc
	s_cbranch_execz .LBB0_63
	v_mul_hi_i32_i24_sdwa v25, sext(v4), s48 dst_sel:DWORD dst_unused:UNUSED_PAD src0_sel:WORD_0 src1_sel:DWORD
	v_mul_i32_i24_sdwa v24, sext(v4), s48 dst_sel:DWORD dst_unused:UNUSED_PAD src0_sel:WORD_0 src1_sel:DWORD
	v_ashrrev_i32_e32 v15, 31, v14
	v_mul_hi_i32_i24_e32 v23, 0x148000, v10
	v_mul_i32_i24_e32 v22, 0x148000, v10
	v_lshl_add_u64 v[24:25], v[24:25], 0, v[14:15]
	v_lshl_add_u64 v[22:23], s[20:21], 0, v[22:23]
	v_or_b32_e32 v24, v24, v16
	v_lshl_add_u64 v[22:23], v[24:25], 3, v[22:23]
	s_waitcnt lgkmcnt(0)
	v_pk_add_f32 v[18:19], v[18:19], v[20:21]
	global_store_dwordx2 v[22:23], v[18:19], off
